# v119 + row-sum adds in the parity copies encoded as VOP2 (4-byte) instead of VOP3 (8-byte)
# speedup vs baseline: 1.0044x; 1.0044x over previous
; template <bool HAS_PV, bool HAS_QK, bool C1> ...
;     s16x4 vlo[2], vhi[2]; bf16x8 ka, qa;
;     if (HAS_PV) {
; #pragma unroll
;         for (int u = 0; u < 2; ++u) { vlo[u] = vtr(vb + vaddr[0] + u * 512); vhi[u] = vtr(vb + vaddr[1] + u * 512); } }
;     if (HAS_QK) { const int ad = C1 ? sub1(kaddr[0]) : kaddr[0]; ka = *(const ATT_LAS bf16x8*)(kb + ad); qa = *(const ATT_LAS bf16x8*)(qb_ + ad);
; #pragma unroll
;         for (int i = 0; i < 16; ++i) Snext[i] = 0.f; }
;     float sa = 0.f, sb = 0.f;
; #pragma unroll
;     for (int g = 0; g < 4; ++g) {
;         s16x4 nlo[2], nhi[2]; bf16x8 nk, nq;
;         if (g < 3) {
;             if (HAS_PV) {
; #pragma unroll
;                 for (int u = 0; u < 2; ++u) { const int off = (2 * ((g + 1) & 1) + u) * 512 + ((g + 1) >> 1) * 4096; nlo[u] = vtr(vb + vaddr[0] + off); nhi[u] = vtr(vb + vaddr[1] + off); } }
;             if (HAS_QK) { const int ad = C1 ? sub1(kaddr[g + 1]) : kaddr[g + 1]; nk = *(const ATT_LAS bf16x8*)(kb + ad); nq = *(const ATT_LAS bf16x8*)(qb_ + ad); }
;         }
;         if (HAS_PV) { const bf16x8 pa = __builtin_bit_cast(bf16x8, pkin[g >> 1]);
; #pragma unroll
;             for (int u = 0; u < 2; ++u) { const bf16x8 vf = __builtin_shufflevector(vlo[u], vhi[u], 0, 1, 2, 3, 4, 5, 6, 7); Opv[2 * (g & 1) + u] = ATT_MFMA(pa, vf, Opv[2 * (g & 1) + u]); } }
;         if (HAS_QK) Snext = ATT_MFMA(ka, qa, Snext);
; #pragma unroll
;         for (int e = 4 * g; e < 4 * g + 4; e += 2) { Scur[e] = __builtin_amdgcn_exp2f(Scur[e] - m); Scur[e + 1] = __builtin_amdgcn_exp2f(Scur[e + 1] - m); sa += Scur[e]; sb += Scur[e + 1]; }
;         if (g & 1) pkout[g >> 1] = (u32x4){cvtpk(Scur[4 * g - 4], Scur[4 * g - 3]), cvtpk(Scur[4 * g - 2], Scur[4 * g - 1]), cvtpk(Scur[4 * g], Scur[4 * g + 1]), cvtpk(Scur[4 * g + 2], Scur[4 * g + 3])};
;         if (g < 3) {
;             if (HAS_PV) {
; #pragma unroll
;                 for (int u = 0; u < 2; ++u) { vlo[u] = nlo[u]; vhi[u] = nhi[u]; } }
;             if (HAS_QK) { ka = nk; qa = nq; }
;         }
;         __builtin_amdgcn_sched_barrier(0);
;     }
;     l += sa + sb;
;     return sa + sb;
; }
; __device__ __forceinline__ void tile_body(bool MASK, const ATT_LAS unsigned char* kb, const ATT_LAS unsigned char* vb, const ATT_LAS unsigned char* qbase, const int (&kaddr)[4], const int (&vaddr)[2], ...
;     ...
;     apply_mask(MASK, Sb, kvrel, r, h); ls = l2;
.Ldma_ns2_p0:
	ds_read_b64_tr_b16 v[8:9], v213 offset:34816
	ds_read_b64_tr_b16 v[6:7], v207 offset:32768
	ds_read_b64_tr_b16 v[146:147], v207 offset:33280
	ds_read_b64_tr_b16 v[174:175], v207 offset:33792
	ds_read_b64_tr_b16 v[182:183], v207 offset:34304
	ds_read_b64_tr_b16 v[148:149], v213 offset:35328
	ds_read_b64_tr_b16 v[176:177], v213 offset:35840
	ds_read_b64_tr_b16 v[184:185], v213 offset:36352
	s_waitcnt lgkmcnt(1)
	v_mfma_f32_32x32x16_bf16 v[34:49], v[2:5], v[6:9], v[34:49]
	ds_read_b128 v[6:9], v203 offset:8192
	ds_read_b128 v[150:153], v217
	ds_read_b128 v[186:189], v204 offset:8192
	ds_read_b128 v[226:229], v219
	v_exp_f32_e32 v15, v158
	v_exp_f32_e32 v239, v160
	v_mfma_f32_32x32x16_bf16 v[50:65], v[2:5], v[146:149], v[50:65]
	v_exp_f32_e32 v14, v159
	v_exp_f32_e32 v238, v161
	s_waitcnt lgkmcnt(2)
	v_mfma_f32_32x32x16_bf16 v[146:161], v[6:9], v[150:153], 0
	v_mfma_f32_32x32x16_bf16 v[66:81], v[2:5], v[174:177], v[66:81]
	ds_read_b64_tr_b16 v[6:7], v207 offset:36864
	ds_read_b64_tr_b16 v[8:9], v213 offset:38912
	ds_read_b64_tr_b16 v[176:177], v213 offset:39424
	ds_read_b64_tr_b16 v[174:175], v207 offset:37376
	ds_read_b128 v[230:233], v205 offset:8192
	ds_read_b128 v[234:237], v221
	v_exp_f32_e32 v241, v162
	v_exp_f32_e32 v240, v163
	v_mfma_f32_32x32x16_bf16 v[82:97], v[2:5], v[182:185], v[82:97]
	v_exp_f32_e32 v243, v164
	v_exp_f32_e32 v242, v165
	v_cvt_pk_bf16_f32 v2, v15, v14
	v_cvt_pk_bf16_f32 v3, v239, v238
	v_cvt_pk_bf16_f32 v4, v241, v240
	s_waitcnt lgkmcnt(2)
	v_mfma_f32_32x32x16_bf16 v[146:161], v[186:189], v[226:229], v[146:161]
	v_cvt_pk_bf16_f32 v5, v243, v242
	v_mfma_f32_32x32x16_bf16 v[34:49], v[10:13], v[6:9], v[34:49]
	ds_read_b64_tr_b16 v[6:7], v207 offset:37888
	ds_read_b64_tr_b16 v[8:9], v213 offset:39936
	ds_read_b64_tr_b16 v[164:165], v213 offset:40448
	ds_read_b64_tr_b16 v[162:163], v207 offset:38400
	ds_read_b128 v[182:185], v206 offset:8192
	ds_read_b128 v[186:189], v223
	v_mfma_f32_32x32x16_bf16 v[50:65], v[10:13], v[174:177], v[50:65]
	v_exp_f32_e32 v175, v166
	v_exp_f32_e32 v174, v167
	v_exp_f32_e32 v167, v168
	v_exp_f32_e32 v166, v169
	s_waitcnt lgkmcnt(2)
	v_mfma_f32_32x32x16_bf16 v[146:161], v[230:233], v[234:237], v[146:161]
	v_mfma_f32_32x32x16_bf16 v[66:81], v[10:13], v[6:9], v[66:81]
	v_exp_f32_e32 v169, v170
	v_exp_f32_e32 v168, v171
	v_exp_f32_e32 v171, v172
	v_exp_f32_e32 v170, v173
	v_mfma_f32_32x32x16_bf16 v[82:97], v[10:13], v[162:165], v[82:97]
	v_cvt_pk_bf16_f32 v6, v175, v174
	v_cvt_pk_bf16_f32 v7, v167, v166
	v_cvt_pk_bf16_f32 v8, v169, v168
	v_cvt_pk_bf16_f32 v9, v171, v170
	v_add_f32_e32 v10, v238, v14
	v_add_f32_e32 v11, v239, v15
	s_waitcnt lgkmcnt(0)
	v_mfma_f32_32x32x16_bf16 v[146:161], v[182:185], v[186:189], v[146:161]
	v_add_f32_e32 v10, v240, v10
	v_add_f32_e32 v11, v241, v11
	v_add_f32_e32 v10, v242, v10
	v_add_f32_e32 v11, v243, v11
	v_add_f32_e32 v10, v174, v10
	v_add_f32_e32 v11, v175, v11
	v_add_f32_e32 v10, v166, v10
	v_add_f32_e32 v11, v167, v11
	v_add_f32_e32 v10, v168, v10
	v_add_f32_e32 v11, v169, v11
	v_add_f32_e32 v10, v170, v10
	v_add_f32_e32 v11, v171, v11
	v_add_f32_e32 v10, v10, v11
	v_cmp_nge_f32_e32 vcc, s58, v10
	s_cbranch_vccnz .Lfix_slow_2

; template <bool HAS_PV, bool HAS_QK, bool C1> ...
;     s16x4 vlo[2], vhi[2]; bf16x8 ka, qa;
;     if (HAS_PV) {
; #pragma unroll
;         for (int u = 0; u < 2; ++u) { vlo[u] = vtr(vb + vaddr[0] + u * 512); vhi[u] = vtr(vb + vaddr[1] + u * 512); } }
;     if (HAS_QK) { const int ad = C1 ? sub1(kaddr[0]) : kaddr[0]; ka = *(const ATT_LAS bf16x8*)(kb + ad); qa = *(const ATT_LAS bf16x8*)(qb_ + ad);
; #pragma unroll
;         for (int i = 0; i < 16; ++i) Snext[i] = 0.f; }
;     float sa = 0.f, sb = 0.f;
; #pragma unroll
;     for (int g = 0; g < 4; ++g) {
;         s16x4 nlo[2], nhi[2]; bf16x8 nk, nq;
;         if (g < 3) {
;             if (HAS_PV) {
; #pragma unroll
;                 for (int u = 0; u < 2; ++u) { const int off = (2 * ((g + 1) & 1) + u) * 512 + ((g + 1) >> 1) * 4096; nlo[u] = vtr(vb + vaddr[0] + off); nhi[u] = vtr(vb + vaddr[1] + off); } }
;             if (HAS_QK) { const int ad = C1 ? sub1(kaddr[g + 1]) : kaddr[g + 1]; nk = *(const ATT_LAS bf16x8*)(kb + ad); nq = *(const ATT_LAS bf16x8*)(qb_ + ad); }
;         }
;         if (HAS_PV) { const bf16x8 pa = __builtin_bit_cast(bf16x8, pkin[g >> 1]);
; #pragma unroll
;             for (int u = 0; u < 2; ++u) { const bf16x8 vf = __builtin_shufflevector(vlo[u], vhi[u], 0, 1, 2, 3, 4, 5, 6, 7); Opv[2 * (g & 1) + u] = ATT_MFMA(pa, vf, Opv[2 * (g & 1) + u]); } }
;         if (HAS_QK) Snext = ATT_MFMA(ka, qa, Snext);
; #pragma unroll
;         for (int e = 4 * g; e < 4 * g + 4; e += 2) { Scur[e] = __builtin_amdgcn_exp2f(Scur[e] - m); Scur[e + 1] = __builtin_amdgcn_exp2f(Scur[e + 1] - m); sa += Scur[e]; sb += Scur[e + 1]; }
;         if (g & 1) pkout[g >> 1] = (u32x4){cvtpk(Scur[4 * g - 4], Scur[4 * g - 3]), cvtpk(Scur[4 * g - 2], Scur[4 * g - 1]), cvtpk(Scur[4 * g], Scur[4 * g + 1]), cvtpk(Scur[4 * g + 2], Scur[4 * g + 3])};
;         if (g < 3) {
;             if (HAS_PV) {
; #pragma unroll
;                 for (int u = 0; u < 2; ++u) { vlo[u] = nlo[u]; vhi[u] = nhi[u]; } }
;             if (HAS_QK) { ka = nk; qa = nq; }
;         }
;         __builtin_amdgcn_sched_barrier(0);
;     }
;     l += sa + sb;
;     return sa + sb;
; }
; __device__ __forceinline__ void tile_body(bool MASK, const ATT_LAS unsigned char* kb, const ATT_LAS unsigned char* vb, const ATT_LAS unsigned char* qbase, const int (&kaddr)[4], const int (&vaddr)[2], ...
;     ...
;     apply_mask(MASK, Sa, kvrel + 32, r, h); ls = l1;
.Ldma_ns3_p0:
	ds_read_b64_tr_b16 v[10:11], v207 offset:32768
	ds_read_b64_tr_b16 v[12:13], v213 offset:34816
	ds_read_b64_tr_b16 v[164:165], v213 offset:35328
	ds_read_b64_tr_b16 v[162:163], v207 offset:33280
	s_waitcnt lgkmcnt(0)
	v_mfma_f32_32x32x16_bf16 v[130:145], v[2:5], v[10:13], v[130:145]
	ds_read_b128 v[166:169], v209 offset:8192
	ds_read_b128 v[170:173], v244
	ds_read_b64_tr_b16 v[10:11], v207 offset:33792
	ds_read_b64_tr_b16 v[12:13], v213 offset:35840
	ds_read_b64_tr_b16 v[184:185], v213 offset:36352
	ds_read_b64_tr_b16 v[182:183], v207 offset:34304
	v_mfma_f32_32x32x16_bf16 v[114:129], v[2:5], v[162:165], v[114:129]
	ds_read_b128 v[186:189], v210 offset:8192
	ds_read_b128 v[224:227], v245
	v_exp_f32_e32 v15, v146
	v_exp_f32_e32 v237, v148
	s_waitcnt lgkmcnt(2)
	v_mfma_f32_32x32x16_bf16 v[162:177], v[166:169], v[170:173], 0
	v_exp_f32_e32 v14, v147
	v_exp_f32_e32 v236, v149
	v_mfma_f32_32x32x16_bf16 v[98:113], v[2:5], v[10:13], v[98:113]
	ds_read_b64_tr_b16 v[146:147], v207 offset:36864
	ds_read_b64_tr_b16 v[148:149], v213 offset:38912
	ds_read_b64_tr_b16 v[230:231], v213 offset:39424
	ds_read_b64_tr_b16 v[228:229], v207 offset:37376
	ds_read_b128 v[10:13], v211 offset:8192
	ds_read_b128 v[232:235], v246
	v_mfma_f32_32x32x16_bf16 v[18:33], v[2:5], v[182:185], v[18:33]
	v_exp_f32_e32 v239, v150
	v_exp_f32_e32 v241, v152
	v_exp_f32_e32 v238, v151
	s_waitcnt lgkmcnt(4)
	v_mfma_f32_32x32x16_bf16 v[162:177], v[186:189], v[224:227], v[162:177]
	v_exp_f32_e32 v240, v153
	v_cvt_pk_bf16_f32 v2, v15, v14
	v_cvt_pk_bf16_f32 v3, v237, v236
	v_cvt_pk_bf16_f32 v4, v239, v238
	v_cvt_pk_bf16_f32 v5, v241, v240
	v_mfma_f32_32x32x16_bf16 v[130:145], v[6:9], v[146:149], v[130:145]
	ds_read_b64_tr_b16 v[146:147], v207 offset:37888
	ds_read_b64_tr_b16 v[148:149], v213 offset:39936
	ds_read_b64_tr_b16 v[152:153], v213 offset:40448
	ds_read_b64_tr_b16 v[150:151], v207 offset:38400
	ds_read_b128 v[182:185], v212 offset:8192
	ds_read_b128 v[186:189], v247
	s_waitcnt lgkmcnt(4)
	v_mfma_f32_32x32x16_bf16 v[114:129], v[6:9], v[228:231], v[114:129]
	v_exp_f32_e32 v225, v154
	v_exp_f32_e32 v224, v155
	v_exp_f32_e32 v155, v156
	v_mfma_f32_32x32x16_bf16 v[162:177], v[10:13], v[232:235], v[162:177]
	v_exp_f32_e32 v154, v157
	v_exp_f32_e32 v157, v158
	v_mfma_f32_32x32x16_bf16 v[98:113], v[6:9], v[146:149], v[98:113]
	v_exp_f32_e32 v156, v159
	v_exp_f32_e32 v147, v160
	v_exp_f32_e32 v146, v161
	v_cvt_pk_bf16_f32 v10, v225, v224
	v_cvt_pk_bf16_f32 v11, v155, v154
	s_waitcnt lgkmcnt(0)
	v_mfma_f32_32x32x16_bf16 v[18:33], v[6:9], v[150:153], v[18:33]
	v_cvt_pk_bf16_f32 v12, v157, v156
	v_cvt_pk_bf16_f32 v13, v147, v146
	v_add_f32_e32 v6, v236, v14
	v_add_f32_e32 v7, v237, v15
	v_add_f32_e32 v6, v238, v6
	v_add_f32_e32 v7, v239, v7
	v_mfma_f32_32x32x16_bf16 v[162:177], v[182:185], v[186:189], v[162:177]
	v_add_f32_e32 v6, v240, v6
	v_add_f32_e32 v7, v241, v7
	v_add_f32_e32 v6, v224, v6
	v_add_f32_e32 v7, v225, v7
	v_add_f32_e32 v6, v154, v6
	v_add_f32_e32 v7, v155, v7
	v_add_f32_e32 v6, v156, v6
	v_add_f32_e32 v7, v157, v7
	v_add_f32_e32 v6, v146, v6
	v_add_f32_e32 v7, v147, v7
	v_add_f32_e32 v6, v6, v7
	v_cmp_nge_f32_e32 vcc, s58, v6
	s_cbranch_vccnz .Lfix_slow_3

; template <bool HAS_PV, bool HAS_QK, bool C1> ...
;     s16x4 vlo[2], vhi[2]; bf16x8 ka, qa;
;     if (HAS_PV) {
; #pragma unroll
;         for (int u = 0; u < 2; ++u) { vlo[u] = vtr(vb + vaddr[0] + u * 512); vhi[u] = vtr(vb + vaddr[1] + u * 512); } }
;     if (HAS_QK) { const int ad = C1 ? sub1(kaddr[0]) : kaddr[0]; ka = *(const ATT_LAS bf16x8*)(kb + ad); qa = *(const ATT_LAS bf16x8*)(qb_ + ad);
; #pragma unroll
;         for (int i = 0; i < 16; ++i) Snext[i] = 0.f; }
;     float sa = 0.f, sb = 0.f;
; #pragma unroll
;     for (int g = 0; g < 4; ++g) {
;         s16x4 nlo[2], nhi[2]; bf16x8 nk, nq;
;         if (g < 3) {
;             if (HAS_PV) {
; #pragma unroll
;                 for (int u = 0; u < 2; ++u) { const int off = (2 * ((g + 1) & 1) + u) * 512 + ((g + 1) >> 1) * 4096; nlo[u] = vtr(vb + vaddr[0] + off); nhi[u] = vtr(vb + vaddr[1] + off); } }
;             if (HAS_QK) { const int ad = C1 ? sub1(kaddr[g + 1]) : kaddr[g + 1]; nk = *(const ATT_LAS bf16x8*)(kb + ad); nq = *(const ATT_LAS bf16x8*)(qb_ + ad); }
;         }
;         if (HAS_PV) { const bf16x8 pa = __builtin_bit_cast(bf16x8, pkin[g >> 1]);
; #pragma unroll
;             for (int u = 0; u < 2; ++u) { const bf16x8 vf = __builtin_shufflevector(vlo[u], vhi[u], 0, 1, 2, 3, 4, 5, 6, 7); Opv[2 * (g & 1) + u] = ATT_MFMA(pa, vf, Opv[2 * (g & 1) + u]); } }
;         if (HAS_QK) Snext = ATT_MFMA(ka, qa, Snext);
; #pragma unroll
;         for (int e = 4 * g; e < 4 * g + 4; e += 2) { Scur[e] = __builtin_amdgcn_exp2f(Scur[e] - m); Scur[e + 1] = __builtin_amdgcn_exp2f(Scur[e + 1] - m); sa += Scur[e]; sb += Scur[e + 1]; }
;         if (g & 1) pkout[g >> 1] = (u32x4){cvtpk(Scur[4 * g - 4], Scur[4 * g - 3]), cvtpk(Scur[4 * g - 2], Scur[4 * g - 1]), cvtpk(Scur[4 * g], Scur[4 * g + 1]), cvtpk(Scur[4 * g + 2], Scur[4 * g + 3])};
;         if (g < 3) {
;             if (HAS_PV) {
; #pragma unroll
;                 for (int u = 0; u < 2; ++u) { vlo[u] = nlo[u]; vhi[u] = nhi[u]; } }
;             if (HAS_QK) { ka = nk; qa = nq; }
;         }
;         __builtin_amdgcn_sched_barrier(0);
;     }
;     l += sa + sb;
;     return sa + sb;
; }
; __device__ __forceinline__ void pv_issue(f32x16 (&O)[4], const u32x4 (&pk)[2], const ATT_LAS unsigned char* vb, const int (&vaddr)[2]) {
; #pragma unroll
;     for (int s_ = 0; s_ < 2; ++s_) { const bf16x8 pa = __builtin_bit_cast(bf16x8, pk[s_]);
; #pragma unroll
.Lns_341_p0:
	ds_read_b64_tr_b16 v[8:9], v213 offset:43008
	ds_read_b64_tr_b16 v[6:7], v207 offset:40960
	ds_read_b64_tr_b16 v[146:147], v207 offset:41472
	ds_read_b64_tr_b16 v[150:151], v207 offset:41984
	ds_read_b64_tr_b16 v[154:155], v207 offset:42496
	ds_read_b64_tr_b16 v[148:149], v213 offset:43520
	ds_read_b64_tr_b16 v[152:153], v213 offset:44032
	ds_read_b64_tr_b16 v[156:157], v213 offset:44544
	s_waitcnt lgkmcnt(1)
	v_mfma_f32_32x32x16_bf16 v[34:49], v[2:5], v[6:9], v[34:49]
	v_exp_f32_e32 v15, v162
	v_exp_f32_e32 v14, v163
	v_exp_f32_e32 v163, v164
	v_mfma_f32_32x32x16_bf16 v[50:65], v[2:5], v[146:149], v[50:65]
	v_exp_f32_e32 v162, v165
	v_mfma_f32_32x32x16_bf16 v[66:81], v[2:5], v[150:153], v[66:81]
	ds_read_b64_tr_b16 v[146:147], v207 offset:45056
	ds_read_b64_tr_b16 v[148:149], v213 offset:47104
	ds_read_b64_tr_b16 v[160:161], v213 offset:47616
	ds_read_b64_tr_b16 v[158:159], v207 offset:45568
	v_exp_f32_e32 v165, v166
	v_exp_f32_e32 v164, v167
	v_exp_f32_e32 v167, v168
	s_waitcnt lgkmcnt(2)
	v_mfma_f32_32x32x16_bf16 v[82:97], v[2:5], v[154:157], v[82:97]
	v_exp_f32_e32 v166, v169
	v_cvt_pk_bf16_f32 v6, v15, v14
	v_cvt_pk_bf16_f32 v7, v163, v162
	v_cvt_pk_bf16_f32 v8, v165, v164
	v_cvt_pk_bf16_f32 v9, v167, v166
	v_mfma_f32_32x32x16_bf16 v[34:49], v[10:13], v[146:149], v[34:49]
	ds_read_b64_tr_b16 v[2:3], v207 offset:46080
	ds_read_b64_tr_b16 v[4:5], v213 offset:48128
	ds_read_b64_tr_b16 v[152:153], v213 offset:48640
	ds_read_b64_tr_b16 v[150:151], v207 offset:46592
	v_exp_f32_e32 v147, v170
	v_exp_f32_e32 v146, v171
	v_exp_f32_e32 v149, v172
	s_waitcnt lgkmcnt(0)
	v_mfma_f32_32x32x16_bf16 v[50:65], v[10:13], v[158:161], v[50:65]
	v_exp_f32_e32 v148, v173
	v_mfma_f32_32x32x16_bf16 v[66:81], v[10:13], v[2:5], v[66:81]
	v_exp_f32_e32 v155, v174
	v_exp_f32_e32 v154, v175
	v_exp_f32_e32 v157, v176
	v_mfma_f32_32x32x16_bf16 v[82:97], v[10:13], v[150:153], v[82:97]
	v_add_f32_e32 v10, v162, v14
	v_add_f32_e32 v11, v163, v15
	v_exp_f32_e32 v156, v177
	v_add_f32_e32 v10, v164, v10
	v_add_f32_e32 v11, v165, v11
	v_cvt_pk_bf16_f32 v2, v147, v146
	v_cvt_pk_bf16_f32 v3, v149, v148
	v_cvt_pk_bf16_f32 v4, v155, v154
	v_cvt_pk_bf16_f32 v5, v157, v156
	v_add_f32_e32 v10, v166, v10
	v_add_f32_e32 v11, v167, v11
	v_add_f32_e32 v10, v146, v10
	v_add_f32_e32 v11, v147, v11
	v_add_f32_e32 v10, v148, v10
	v_add_f32_e32 v11, v149, v11
	v_add_f32_e32 v10, v154, v10
	v_add_f32_e32 v11, v155, v11
	v_add_f32_e32 v10, v156, v10
	v_add_f32_e32 v11, v157, v11
	v_add_f32_e32 v10, v10, v11
	v_cmp_nge_f32_e32 vcc, s58, v10
	s_cbranch_vccnz .Lfix_slow_4
	v_add_f32_e32 v224, v181, v10
	ds_read_b64_tr_b16 v[12:13], v213 offset:43008
	ds_read_b64_tr_b16 v[10:11], v207 offset:40960
	ds_read_b64_tr_b16 v[146:147], v207 offset:41472
	ds_read_b64_tr_b16 v[150:151], v207 offset:41984
	ds_read_b64_tr_b16 v[154:155], v207 offset:42496
	ds_read_b64_tr_b16 v[148:149], v213 offset:43520
	ds_read_b64_tr_b16 v[152:153], v213 offset:44032
	ds_read_b64_tr_b16 v[156:157], v213 offset:44544
	ds_read_b64_tr_b16 v[160:161], v213 offset:47104
	ds_read_b64_tr_b16 v[158:159], v207 offset:45056
	ds_read_b64_tr_b16 v[162:163], v207 offset:45568
	ds_read_b64_tr_b16 v[166:167], v207 offset:46080
	ds_read_b64_tr_b16 v[170:171], v207 offset:46592
	ds_read_b64_tr_b16 v[164:165], v213 offset:47616
	ds_read_b64_tr_b16 v[168:169], v213 offset:48128
	s_waitcnt lgkmcnt(7)
	v_mfma_f32_32x32x16_bf16 v[130:145], v[6:9], v[10:13], v[130:145]
	v_mfma_f32_32x32x16_bf16 v[114:129], v[6:9], v[146:149], v[114:129]
	v_mfma_f32_32x32x16_bf16 v[98:113], v[6:9], v[150:153], v[98:113]
	v_mfma_f32_32x32x16_bf16 v[18:33], v[6:9], v[154:157], v[18:33]
	ds_read_b64_tr_b16 v[172:173], v213 offset:48640
	s_waitcnt lgkmcnt(0)
	v_mfma_f32_32x32x16_bf16 v[130:145], v[2:5], v[158:161], v[130:145]
	v_mfma_f32_32x32x16_bf16 v[114:129], v[2:5], v[162:165], v[114:129]
	v_mfma_f32_32x32x16_bf16 v[98:113], v[2:5], v[166:169], v[98:113]
	v_mfma_f32_32x32x16_bf16 v[18:33], v[2:5], v[170:173], v[18:33]
	s_add_i32 s80, s80, 64
	s_add_u32 s94, s94, 0x20000
	s_addc_u32 s95, s95, 0
	s_waitcnt vmcnt(0)
	s_add_u32 s92, s92, 0x20000
	s_addc_u32 s93, s93, 0
	s_cmp_eq_u32 s76, s79
	v_subrev_u32_e32 v214, 64, v214
	s_barrier
	s_cbranch_scc1 .LBB0_352

; template <bool HAS_PV, bool HAS_QK, bool C1> ...
;     s16x4 vlo[2], vhi[2]; bf16x8 ka, qa;
;     if (HAS_PV) {
; #pragma unroll
;         for (int u = 0; u < 2; ++u) { vlo[u] = vtr(vb + vaddr[0] + u * 512); vhi[u] = vtr(vb + vaddr[1] + u * 512); } }
;     if (HAS_QK) { const int ad = C1 ? sub1(kaddr[0]) : kaddr[0]; ka = *(const ATT_LAS bf16x8*)(kb + ad); qa = *(const ATT_LAS bf16x8*)(qb_ + ad);
; #pragma unroll
;         for (int i = 0; i < 16; ++i) Snext[i] = 0.f; }
;     float sa = 0.f, sb = 0.f;
; #pragma unroll
;     for (int g = 0; g < 4; ++g) {
;         s16x4 nlo[2], nhi[2]; bf16x8 nk, nq;
;         if (g < 3) {
;             if (HAS_PV) {
; #pragma unroll
;                 for (int u = 0; u < 2; ++u) { const int off = (2 * ((g + 1) & 1) + u) * 512 + ((g + 1) >> 1) * 4096; nlo[u] = vtr(vb + vaddr[0] + off); nhi[u] = vtr(vb + vaddr[1] + off); } }
;             if (HAS_QK) { const int ad = C1 ? sub1(kaddr[g + 1]) : kaddr[g + 1]; nk = *(const ATT_LAS bf16x8*)(kb + ad); nq = *(const ATT_LAS bf16x8*)(qb_ + ad); }
;         }
;         if (HAS_PV) { const bf16x8 pa = __builtin_bit_cast(bf16x8, pkin[g >> 1]);
; #pragma unroll
;             for (int u = 0; u < 2; ++u) { const bf16x8 vf = __builtin_shufflevector(vlo[u], vhi[u], 0, 1, 2, 3, 4, 5, 6, 7); Opv[2 * (g & 1) + u] = ATT_MFMA(pa, vf, Opv[2 * (g & 1) + u]); } }
;         if (HAS_QK) Snext = ATT_MFMA(ka, qa, Snext);
; #pragma unroll
;         for (int e = 4 * g; e < 4 * g + 4; e += 2) { Scur[e] = __builtin_amdgcn_exp2f(Scur[e] - m); Scur[e + 1] = __builtin_amdgcn_exp2f(Scur[e + 1] - m); sa += Scur[e]; sb += Scur[e + 1]; }
;         if (g & 1) pkout[g >> 1] = (u32x4){cvtpk(Scur[4 * g - 4], Scur[4 * g - 3]), cvtpk(Scur[4 * g - 2], Scur[4 * g - 1]), cvtpk(Scur[4 * g], Scur[4 * g + 1]), cvtpk(Scur[4 * g + 2], Scur[4 * g + 3])};
;         if (g < 3) {
;             if (HAS_PV) {
; #pragma unroll
;                 for (int u = 0; u < 2; ++u) { vlo[u] = nlo[u]; vhi[u] = nhi[u]; } }
;             if (HAS_QK) { ka = nk; qa = nq; }
;         }
;         __builtin_amdgcn_sched_barrier(0);
;     }
;     l += sa + sb;
;     return sa + sb;
; }
; __device__ __forceinline__ void tile_body(bool MASK, const ATT_LAS unsigned char* kb, const ATT_LAS unsigned char* vb, const ATT_LAS unsigned char* qbase, const int (&kaddr)[4], const int (&vaddr)[2], ...
;     ...
;     apply_mask(MASK, Sb, kvrel, r, h); ls = l2;
.Ldma_ns2_p1:
	ds_read_b64_tr_b16 v[8:9], v213 offset:51200
	ds_read_b64_tr_b16 v[6:7], v207 offset:49152
	ds_read_b64_tr_b16 v[146:147], v207 offset:49664
	ds_read_b64_tr_b16 v[174:175], v207 offset:50176
	ds_read_b64_tr_b16 v[182:183], v207 offset:50688
	ds_read_b64_tr_b16 v[148:149], v213 offset:51712
	ds_read_b64_tr_b16 v[176:177], v213 offset:52224
	ds_read_b64_tr_b16 v[184:185], v213 offset:52736
	s_waitcnt lgkmcnt(1)
	v_mfma_f32_32x32x16_bf16 v[34:49], v[2:5], v[6:9], v[34:49]
	ds_read_b128 v[6:9], v203 offset:24576
	ds_read_b128 v[150:153], v217
	ds_read_b128 v[186:189], v204 offset:24576
	ds_read_b128 v[226:229], v219
	v_exp_f32_e32 v15, v158
	v_exp_f32_e32 v239, v160
	v_mfma_f32_32x32x16_bf16 v[50:65], v[2:5], v[146:149], v[50:65]
	v_exp_f32_e32 v14, v159
	v_exp_f32_e32 v238, v161
	s_waitcnt lgkmcnt(2)
	v_mfma_f32_32x32x16_bf16 v[146:161], v[6:9], v[150:153], 0
	v_mfma_f32_32x32x16_bf16 v[66:81], v[2:5], v[174:177], v[66:81]
	ds_read_b64_tr_b16 v[6:7], v207 offset:53248
	ds_read_b64_tr_b16 v[8:9], v213 offset:55296
	ds_read_b64_tr_b16 v[176:177], v213 offset:55808
	ds_read_b64_tr_b16 v[174:175], v207 offset:53760
	ds_read_b128 v[230:233], v205 offset:24576
	ds_read_b128 v[234:237], v221
	v_exp_f32_e32 v241, v162
	v_exp_f32_e32 v240, v163
	v_mfma_f32_32x32x16_bf16 v[82:97], v[2:5], v[182:185], v[82:97]
	v_exp_f32_e32 v243, v164
	v_exp_f32_e32 v242, v165
	v_cvt_pk_bf16_f32 v2, v15, v14
	v_cvt_pk_bf16_f32 v3, v239, v238
	v_cvt_pk_bf16_f32 v4, v241, v240
	s_waitcnt lgkmcnt(2)
	v_mfma_f32_32x32x16_bf16 v[146:161], v[186:189], v[226:229], v[146:161]
	v_cvt_pk_bf16_f32 v5, v243, v242
	v_mfma_f32_32x32x16_bf16 v[34:49], v[10:13], v[6:9], v[34:49]
	ds_read_b64_tr_b16 v[6:7], v207 offset:54272
	ds_read_b64_tr_b16 v[8:9], v213 offset:56320
	ds_read_b64_tr_b16 v[164:165], v213 offset:56832
	ds_read_b64_tr_b16 v[162:163], v207 offset:54784
	ds_read_b128 v[182:185], v206 offset:24576
	ds_read_b128 v[186:189], v223
	v_mfma_f32_32x32x16_bf16 v[50:65], v[10:13], v[174:177], v[50:65]
	v_exp_f32_e32 v175, v166
	v_exp_f32_e32 v174, v167
	v_exp_f32_e32 v167, v168
	v_exp_f32_e32 v166, v169
	s_waitcnt lgkmcnt(2)
	v_mfma_f32_32x32x16_bf16 v[146:161], v[230:233], v[234:237], v[146:161]
	v_mfma_f32_32x32x16_bf16 v[66:81], v[10:13], v[6:9], v[66:81]
	v_exp_f32_e32 v169, v170
	v_exp_f32_e32 v168, v171
	v_exp_f32_e32 v171, v172
	v_exp_f32_e32 v170, v173
	v_mfma_f32_32x32x16_bf16 v[82:97], v[10:13], v[162:165], v[82:97]
	v_cvt_pk_bf16_f32 v6, v175, v174
	v_cvt_pk_bf16_f32 v7, v167, v166
	v_cvt_pk_bf16_f32 v8, v169, v168
	v_cvt_pk_bf16_f32 v9, v171, v170
	v_add_f32_e32 v10, v238, v14
	v_add_f32_e32 v11, v239, v15
	s_waitcnt lgkmcnt(0)
	v_mfma_f32_32x32x16_bf16 v[146:161], v[182:185], v[186:189], v[146:161]
	v_add_f32_e32 v10, v240, v10
	v_add_f32_e32 v11, v241, v11
	v_add_f32_e32 v10, v242, v10
	v_add_f32_e32 v11, v243, v11
	v_add_f32_e32 v10, v174, v10
	v_add_f32_e32 v11, v175, v11
	v_add_f32_e32 v10, v166, v10
	v_add_f32_e32 v11, v167, v11
	v_add_f32_e32 v10, v168, v10
	v_add_f32_e32 v11, v169, v11
	v_add_f32_e32 v10, v170, v10
	v_add_f32_e32 v11, v171, v11
	v_add_f32_e32 v10, v10, v11
	v_cmp_nge_f32_e32 vcc, s58, v10
	s_cbranch_vccnz .Lfix_slow_2

; template <bool HAS_PV, bool HAS_QK, bool C1> ...
;     s16x4 vlo[2], vhi[2]; bf16x8 ka, qa;
;     if (HAS_PV) {
; #pragma unroll
;         for (int u = 0; u < 2; ++u) { vlo[u] = vtr(vb + vaddr[0] + u * 512); vhi[u] = vtr(vb + vaddr[1] + u * 512); } }
;     if (HAS_QK) { const int ad = C1 ? sub1(kaddr[0]) : kaddr[0]; ka = *(const ATT_LAS bf16x8*)(kb + ad); qa = *(const ATT_LAS bf16x8*)(qb_ + ad);
; #pragma unroll
;         for (int i = 0; i < 16; ++i) Snext[i] = 0.f; }
;     float sa = 0.f, sb = 0.f;
; #pragma unroll
;     for (int g = 0; g < 4; ++g) {
;         s16x4 nlo[2], nhi[2]; bf16x8 nk, nq;
;         if (g < 3) {
;             if (HAS_PV) {
; #pragma unroll
;                 for (int u = 0; u < 2; ++u) { const int off = (2 * ((g + 1) & 1) + u) * 512 + ((g + 1) >> 1) * 4096; nlo[u] = vtr(vb + vaddr[0] + off); nhi[u] = vtr(vb + vaddr[1] + off); } }
;             if (HAS_QK) { const int ad = C1 ? sub1(kaddr[g + 1]) : kaddr[g + 1]; nk = *(const ATT_LAS bf16x8*)(kb + ad); nq = *(const ATT_LAS bf16x8*)(qb_ + ad); }
;         }
;         if (HAS_PV) { const bf16x8 pa = __builtin_bit_cast(bf16x8, pkin[g >> 1]);
; #pragma unroll
;             for (int u = 0; u < 2; ++u) { const bf16x8 vf = __builtin_shufflevector(vlo[u], vhi[u], 0, 1, 2, 3, 4, 5, 6, 7); Opv[2 * (g & 1) + u] = ATT_MFMA(pa, vf, Opv[2 * (g & 1) + u]); } }
;         if (HAS_QK) Snext = ATT_MFMA(ka, qa, Snext);
; #pragma unroll
;         for (int e = 4 * g; e < 4 * g + 4; e += 2) { Scur[e] = __builtin_amdgcn_exp2f(Scur[e] - m); Scur[e + 1] = __builtin_amdgcn_exp2f(Scur[e + 1] - m); sa += Scur[e]; sb += Scur[e + 1]; }
;         if (g & 1) pkout[g >> 1] = (u32x4){cvtpk(Scur[4 * g - 4], Scur[4 * g - 3]), cvtpk(Scur[4 * g - 2], Scur[4 * g - 1]), cvtpk(Scur[4 * g], Scur[4 * g + 1]), cvtpk(Scur[4 * g + 2], Scur[4 * g + 3])};
;         if (g < 3) {
;             if (HAS_PV) {
; #pragma unroll
;                 for (int u = 0; u < 2; ++u) { vlo[u] = nlo[u]; vhi[u] = nhi[u]; } }
;             if (HAS_QK) { ka = nk; qa = nq; }
;         }
;         __builtin_amdgcn_sched_barrier(0);
;     }
;     l += sa + sb;
;     return sa + sb;
; }
; __device__ __forceinline__ void tile_body(bool MASK, const ATT_LAS unsigned char* kb, const ATT_LAS unsigned char* vb, const ATT_LAS unsigned char* qbase, const int (&kaddr)[4], const int (&vaddr)[2], ...
;     ...
;     apply_mask(MASK, Sa, kvrel + 32, r, h); ls = l1;
.Ldma_ns3_p1:
	ds_read_b64_tr_b16 v[10:11], v207 offset:49152
	ds_read_b64_tr_b16 v[12:13], v213 offset:51200
	ds_read_b64_tr_b16 v[164:165], v213 offset:51712
	ds_read_b64_tr_b16 v[162:163], v207 offset:49664
	s_waitcnt lgkmcnt(0)
	v_mfma_f32_32x32x16_bf16 v[130:145], v[2:5], v[10:13], v[130:145]
	ds_read_b128 v[166:169], v209 offset:24576
	ds_read_b128 v[170:173], v244
	ds_read_b64_tr_b16 v[10:11], v207 offset:50176
	ds_read_b64_tr_b16 v[12:13], v213 offset:52224
	ds_read_b64_tr_b16 v[184:185], v213 offset:52736
	ds_read_b64_tr_b16 v[182:183], v207 offset:50688
	v_mfma_f32_32x32x16_bf16 v[114:129], v[2:5], v[162:165], v[114:129]
	ds_read_b128 v[186:189], v210 offset:24576
	ds_read_b128 v[224:227], v245
	v_exp_f32_e32 v15, v146
	v_exp_f32_e32 v237, v148
	s_waitcnt lgkmcnt(2)
	v_mfma_f32_32x32x16_bf16 v[162:177], v[166:169], v[170:173], 0
	v_exp_f32_e32 v14, v147
	v_exp_f32_e32 v236, v149
	v_mfma_f32_32x32x16_bf16 v[98:113], v[2:5], v[10:13], v[98:113]
	ds_read_b64_tr_b16 v[146:147], v207 offset:53248
	ds_read_b64_tr_b16 v[148:149], v213 offset:55296
	ds_read_b64_tr_b16 v[230:231], v213 offset:55808
	ds_read_b64_tr_b16 v[228:229], v207 offset:53760
	ds_read_b128 v[10:13], v211 offset:24576
	ds_read_b128 v[232:235], v246
	v_mfma_f32_32x32x16_bf16 v[18:33], v[2:5], v[182:185], v[18:33]
	v_exp_f32_e32 v239, v150
	v_exp_f32_e32 v241, v152
	v_exp_f32_e32 v238, v151
	s_waitcnt lgkmcnt(4)
	v_mfma_f32_32x32x16_bf16 v[162:177], v[186:189], v[224:227], v[162:177]
	v_exp_f32_e32 v240, v153
	v_cvt_pk_bf16_f32 v2, v15, v14
	v_cvt_pk_bf16_f32 v3, v237, v236
	v_cvt_pk_bf16_f32 v4, v239, v238
	v_cvt_pk_bf16_f32 v5, v241, v240
	v_mfma_f32_32x32x16_bf16 v[130:145], v[6:9], v[146:149], v[130:145]
	ds_read_b64_tr_b16 v[146:147], v207 offset:54272
	ds_read_b64_tr_b16 v[148:149], v213 offset:56320
	ds_read_b64_tr_b16 v[152:153], v213 offset:56832
	ds_read_b64_tr_b16 v[150:151], v207 offset:54784
	ds_read_b128 v[182:185], v212 offset:24576
	ds_read_b128 v[186:189], v247
	s_waitcnt lgkmcnt(4)
	v_mfma_f32_32x32x16_bf16 v[114:129], v[6:9], v[228:231], v[114:129]
	v_exp_f32_e32 v225, v154
	v_exp_f32_e32 v224, v155
	v_exp_f32_e32 v155, v156
	v_mfma_f32_32x32x16_bf16 v[162:177], v[10:13], v[232:235], v[162:177]
	v_exp_f32_e32 v154, v157
	v_exp_f32_e32 v157, v158
	v_mfma_f32_32x32x16_bf16 v[98:113], v[6:9], v[146:149], v[98:113]
	v_exp_f32_e32 v156, v159
	v_exp_f32_e32 v147, v160
	v_exp_f32_e32 v146, v161
	v_cvt_pk_bf16_f32 v10, v225, v224
	v_cvt_pk_bf16_f32 v11, v155, v154
	s_waitcnt lgkmcnt(0)
	v_mfma_f32_32x32x16_bf16 v[18:33], v[6:9], v[150:153], v[18:33]
	v_cvt_pk_bf16_f32 v12, v157, v156
	v_cvt_pk_bf16_f32 v13, v147, v146
	v_add_f32_e32 v6, v236, v14
	v_add_f32_e32 v7, v237, v15
	v_add_f32_e32 v6, v238, v6
	v_add_f32_e32 v7, v239, v7
	v_mfma_f32_32x32x16_bf16 v[162:177], v[182:185], v[186:189], v[162:177]
	v_add_f32_e32 v6, v240, v6
	v_add_f32_e32 v7, v241, v7
	v_add_f32_e32 v6, v224, v6
	v_add_f32_e32 v7, v225, v7
	v_add_f32_e32 v6, v154, v6
	v_add_f32_e32 v7, v155, v7
	v_add_f32_e32 v6, v156, v6
	v_add_f32_e32 v7, v157, v7
	v_add_f32_e32 v6, v146, v6
	v_add_f32_e32 v7, v147, v7
	v_add_f32_e32 v6, v6, v7
	v_cmp_nge_f32_e32 vcc, s58, v6
	s_cbranch_vccnz .Lfix_slow_3

; template <bool HAS_PV, bool HAS_QK, bool C1> ...
;     s16x4 vlo[2], vhi[2]; bf16x8 ka, qa;
;     if (HAS_PV) {
; #pragma unroll
;         for (int u = 0; u < 2; ++u) { vlo[u] = vtr(vb + vaddr[0] + u * 512); vhi[u] = vtr(vb + vaddr[1] + u * 512); } }
;     if (HAS_QK) { const int ad = C1 ? sub1(kaddr[0]) : kaddr[0]; ka = *(const ATT_LAS bf16x8*)(kb + ad); qa = *(const ATT_LAS bf16x8*)(qb_ + ad);
; #pragma unroll
;         for (int i = 0; i < 16; ++i) Snext[i] = 0.f; }
;     float sa = 0.f, sb = 0.f;
; #pragma unroll
;     for (int g = 0; g < 4; ++g) {
;         s16x4 nlo[2], nhi[2]; bf16x8 nk, nq;
;         if (g < 3) {
;             if (HAS_PV) {
; #pragma unroll
;                 for (int u = 0; u < 2; ++u) { const int off = (2 * ((g + 1) & 1) + u) * 512 + ((g + 1) >> 1) * 4096; nlo[u] = vtr(vb + vaddr[0] + off); nhi[u] = vtr(vb + vaddr[1] + off); } }
;             if (HAS_QK) { const int ad = C1 ? sub1(kaddr[g + 1]) : kaddr[g + 1]; nk = *(const ATT_LAS bf16x8*)(kb + ad); nq = *(const ATT_LAS bf16x8*)(qb_ + ad); }
;         }
;         if (HAS_PV) { const bf16x8 pa = __builtin_bit_cast(bf16x8, pkin[g >> 1]);
; #pragma unroll
;             for (int u = 0; u < 2; ++u) { const bf16x8 vf = __builtin_shufflevector(vlo[u], vhi[u], 0, 1, 2, 3, 4, 5, 6, 7); Opv[2 * (g & 1) + u] = ATT_MFMA(pa, vf, Opv[2 * (g & 1) + u]); } }
;         if (HAS_QK) Snext = ATT_MFMA(ka, qa, Snext);
; #pragma unroll
;         for (int e = 4 * g; e < 4 * g + 4; e += 2) { Scur[e] = __builtin_amdgcn_exp2f(Scur[e] - m); Scur[e + 1] = __builtin_amdgcn_exp2f(Scur[e + 1] - m); sa += Scur[e]; sb += Scur[e + 1]; }
;         if (g & 1) pkout[g >> 1] = (u32x4){cvtpk(Scur[4 * g - 4], Scur[4 * g - 3]), cvtpk(Scur[4 * g - 2], Scur[4 * g - 1]), cvtpk(Scur[4 * g], Scur[4 * g + 1]), cvtpk(Scur[4 * g + 2], Scur[4 * g + 3])};
;         if (g < 3) {
;             if (HAS_PV) {
; #pragma unroll
;                 for (int u = 0; u < 2; ++u) { vlo[u] = nlo[u]; vhi[u] = nhi[u]; } }
;             if (HAS_QK) { ka = nk; qa = nq; }
;         }
;         __builtin_amdgcn_sched_barrier(0);
;     }
;     l += sa + sb;
;     return sa + sb;
; }
; __device__ __forceinline__ void pv_issue(f32x16 (&O)[4], const u32x4 (&pk)[2], const ATT_LAS unsigned char* vb, const int (&vaddr)[2]) {
; #pragma unroll
;     for (int s_ = 0; s_ < 2; ++s_) { const bf16x8 pa = __builtin_bit_cast(bf16x8, pk[s_]);
; #pragma unroll
.Lns_341_p1:
	ds_read_b64_tr_b16 v[8:9], v213 offset:59392
	ds_read_b64_tr_b16 v[6:7], v207 offset:57344
	ds_read_b64_tr_b16 v[146:147], v207 offset:57856
	ds_read_b64_tr_b16 v[150:151], v207 offset:58368
	ds_read_b64_tr_b16 v[154:155], v207 offset:58880
	ds_read_b64_tr_b16 v[148:149], v213 offset:59904
	ds_read_b64_tr_b16 v[152:153], v213 offset:60416
	ds_read_b64_tr_b16 v[156:157], v213 offset:60928
	s_waitcnt lgkmcnt(1)
	v_mfma_f32_32x32x16_bf16 v[34:49], v[2:5], v[6:9], v[34:49]
	v_exp_f32_e32 v15, v162
	v_exp_f32_e32 v14, v163
	v_exp_f32_e32 v163, v164
	v_mfma_f32_32x32x16_bf16 v[50:65], v[2:5], v[146:149], v[50:65]
	v_exp_f32_e32 v162, v165
	v_mfma_f32_32x32x16_bf16 v[66:81], v[2:5], v[150:153], v[66:81]
	ds_read_b64_tr_b16 v[146:147], v207 offset:61440
	ds_read_b64_tr_b16 v[148:149], v213 offset:63488
	ds_read_b64_tr_b16 v[160:161], v213 offset:64000
	ds_read_b64_tr_b16 v[158:159], v207 offset:61952
	v_exp_f32_e32 v165, v166
	v_exp_f32_e32 v164, v167
	v_exp_f32_e32 v167, v168
	s_waitcnt lgkmcnt(2)
	v_mfma_f32_32x32x16_bf16 v[82:97], v[2:5], v[154:157], v[82:97]
	v_exp_f32_e32 v166, v169
	v_cvt_pk_bf16_f32 v6, v15, v14
	v_cvt_pk_bf16_f32 v7, v163, v162
	v_cvt_pk_bf16_f32 v8, v165, v164
	v_cvt_pk_bf16_f32 v9, v167, v166
	v_mfma_f32_32x32x16_bf16 v[34:49], v[10:13], v[146:149], v[34:49]
	ds_read_b64_tr_b16 v[2:3], v207 offset:62464
	ds_read_b64_tr_b16 v[4:5], v213 offset:64512
	ds_read_b64_tr_b16 v[152:153], v213 offset:65024
	ds_read_b64_tr_b16 v[150:151], v207 offset:62976
	v_exp_f32_e32 v147, v170
	v_exp_f32_e32 v146, v171
	v_exp_f32_e32 v149, v172
	s_waitcnt lgkmcnt(0)
	v_mfma_f32_32x32x16_bf16 v[50:65], v[10:13], v[158:161], v[50:65]
	v_exp_f32_e32 v148, v173
	v_mfma_f32_32x32x16_bf16 v[66:81], v[10:13], v[2:5], v[66:81]
	v_exp_f32_e32 v155, v174
	v_exp_f32_e32 v154, v175
	v_exp_f32_e32 v157, v176
	v_mfma_f32_32x32x16_bf16 v[82:97], v[10:13], v[150:153], v[82:97]
	v_add_f32_e32 v10, v162, v14
	v_add_f32_e32 v11, v163, v15
	v_exp_f32_e32 v156, v177
	v_add_f32_e32 v10, v164, v10
	v_add_f32_e32 v11, v165, v11
	v_cvt_pk_bf16_f32 v2, v147, v146
	v_cvt_pk_bf16_f32 v3, v149, v148
	v_cvt_pk_bf16_f32 v4, v155, v154
	v_cvt_pk_bf16_f32 v5, v157, v156
	v_add_f32_e32 v10, v166, v10
	v_add_f32_e32 v11, v167, v11
	v_add_f32_e32 v10, v146, v10
	v_add_f32_e32 v11, v147, v11
	v_add_f32_e32 v10, v148, v10
	v_add_f32_e32 v11, v149, v11
	v_add_f32_e32 v10, v154, v10
	v_add_f32_e32 v11, v155, v11
	v_add_f32_e32 v10, v156, v10
	v_add_f32_e32 v11, v157, v11
	v_add_f32_e32 v10, v10, v11
	v_cmp_nge_f32_e32 vcc, s58, v10
	s_cbranch_vccnz .Lfix_slow_4
	v_add_f32_e32 v224, v181, v10
	ds_read_b64_tr_b16 v[12:13], v213 offset:59392
	ds_read_b64_tr_b16 v[10:11], v207 offset:57344
	ds_read_b64_tr_b16 v[146:147], v207 offset:57856
	ds_read_b64_tr_b16 v[150:151], v207 offset:58368
	ds_read_b64_tr_b16 v[154:155], v207 offset:58880
	ds_read_b64_tr_b16 v[148:149], v213 offset:59904
	ds_read_b64_tr_b16 v[152:153], v213 offset:60416
	ds_read_b64_tr_b16 v[156:157], v213 offset:60928
	ds_read_b64_tr_b16 v[160:161], v213 offset:63488
	ds_read_b64_tr_b16 v[158:159], v207 offset:61440
	ds_read_b64_tr_b16 v[162:163], v207 offset:61952
	ds_read_b64_tr_b16 v[166:167], v207 offset:62464
	ds_read_b64_tr_b16 v[170:171], v207 offset:62976
	ds_read_b64_tr_b16 v[164:165], v213 offset:64000
	ds_read_b64_tr_b16 v[168:169], v213 offset:64512
	s_waitcnt lgkmcnt(7)
	v_mfma_f32_32x32x16_bf16 v[130:145], v[6:9], v[10:13], v[130:145]
	v_mfma_f32_32x32x16_bf16 v[114:129], v[6:9], v[146:149], v[114:129]
	v_mfma_f32_32x32x16_bf16 v[98:113], v[6:9], v[150:153], v[98:113]
	v_mfma_f32_32x32x16_bf16 v[18:33], v[6:9], v[154:157], v[18:33]
	ds_read_b64_tr_b16 v[172:173], v213 offset:65024
	s_waitcnt lgkmcnt(0)
	v_mfma_f32_32x32x16_bf16 v[130:145], v[2:5], v[158:161], v[130:145]
	v_mfma_f32_32x32x16_bf16 v[114:129], v[2:5], v[162:165], v[114:129]
	v_mfma_f32_32x32x16_bf16 v[98:113], v[2:5], v[166:169], v[98:113]
	v_mfma_f32_32x32x16_bf16 v[18:33], v[2:5], v[170:173], v[18:33]
	s_add_i32 s80, s80, 64
	s_add_u32 s94, s94, 0x20000
	s_addc_u32 s95, s95, 0
	s_waitcnt vmcnt(0)
	s_add_u32 s92, s92, 0x20000
	s_addc_u32 s93, s93, 0
	s_cmp_eq_u32 s76, s79
	v_subrev_u32_e32 v214, 64, v214
	s_barrier
	s_cbranch_scc0 .Lhead_p0
	s_branch .LBB0_352
